# v39 + FoX: serial row-max / lazy-rescale branch-test chain between QK and PV blocks shortened by 3 instructions per step (guide 7.12): max of the two permlane32_swap copies, redundant second compare r
# baseline (speedup 1.0000x reference)
.Lfx_hoisted_8013:
	ds_read_b128 v[198:201], v193
	ds_read_b128 v[206:209], v193 offset:512
	s_waitcnt lgkmcnt(1)
	v_mfma_f32_32x32x16_bf16 v[80:95], v[198:201], v[202:205], v[80:95]
	ds_read_b128 v[198:201], v193 offset:2080
	v_max3_f32 v197, v48, s94, v49
	v_max3_f32 v197, v197, v50, v51
	s_waitcnt lgkmcnt(1)
	v_mfma_f32_32x32x16_bf16 v[64:79], v[206:209], v[202:205], v[64:79]
	ds_read_b128 v[202:205], v193 offset:2592
	ds_read_b128 v[206:209], v189 offset:62464
	v_max3_f32 v197, v197, v52, v53
	v_max3_f32 v197, v197, v54, v55
	s_waitcnt lgkmcnt(2)
	v_mfma_f32_32x32x16_bf16 v[80:95], v[198:201], v[210:213], v[80:95]
	ds_read_b128 v[198:201], v193 offset:4160
	v_max3_f32 v197, v197, v56, v57
	v_max3_f32 v197, v197, v58, v59
	s_waitcnt lgkmcnt(2)
	v_mfma_f32_32x32x16_bf16 v[64:79], v[202:205], v[210:213], v[64:79]
	ds_read_b128 v[202:205], v193 offset:4672
	ds_read_b128 v[210:213], v189 offset:63488
	v_max3_f32 v197, v197, v60, v61
	v_max3_f32 v197, v197, v62, v63
	s_waitcnt lgkmcnt(2)
	v_mfma_f32_32x32x16_bf16 v[80:95], v[198:201], v[206:209], v[80:95]
	ds_read_b128 v[198:201], v193 offset:6240
	v_max3_f32 v197, v197, v32, v33
	v_max3_f32 v197, v197, v34, v35
	s_waitcnt lgkmcnt(2)
	v_mfma_f32_32x32x16_bf16 v[64:79], v[202:205], v[206:209], v[64:79]
	ds_read_b128 v[202:205], v193 offset:6752
	v_max3_f32 v197, v197, v36, v37
	v_max3_f32 v197, v197, v38, v39
	s_waitcnt lgkmcnt(1)
	v_mfma_f32_32x32x16_bf16 v[80:95], v[198:201], v[210:213], v[80:95]
	v_max3_f32 v197, v197, v40, v41
	v_max3_f32 v197, v197, v42, v43
	s_waitcnt lgkmcnt(0)
	v_mfma_f32_32x32x16_bf16 v[64:79], v[202:205], v[210:213], v[64:79]
	v_max3_f32 v197, v197, v44, v45
	v_max3_f32 v197, v197, v46, v47
	v_mov_b32_e32 v198, v197
	v_mov_b32_e32 v199, v197
	s_nop 1
	v_permlane32_swap_b32_e32 v198, v199
	v_max_f32_e32 v197, v198, v199
	v_add_f32_e32 v198, 0x40c00000, v196
	v_cmp_gt_f32_e32 vcc, v197, v198
	s_nop 1
	v_cndmask_b32_e32 v236, v196, v197, vcc
	v_sub_f32_e32 v197, v196, v236
	v_exp_f32_e32 v197, v197
	s_cbranch_vccz .LBB0_343
	s_and_saveexec_b64 s[48:49], s[36:37]
	ds_write_b32 v176, v197 offset:58112
	s_or_b64 exec, exec, s[48:49]
	v_add_u32_e32 v196, s75, v108
	ds_read_b128 v[198:201], v196 offset:58208
	ds_read_b128 v[202:205], v196 offset:58176
	ds_read_b128 v[206:209], v196 offset:58144
	ds_read_b128 v[210:213], v196 offset:58112
	s_waitcnt lgkmcnt(3)
	v_pk_mul_f32 v[28:29], v[28:29], v[198:199]
	s_waitcnt lgkmcnt(2)
	v_pk_mul_f32 v[24:25], v[24:25], v[202:203]
	s_waitcnt lgkmcnt(1)
	v_pk_mul_f32 v[20:21], v[20:21], v[206:207]
	s_waitcnt lgkmcnt(0)
	v_pk_mul_f32 v[16:17], v[16:17], v[210:211]
	v_pk_mul_f32 v[12:13], v[12:13], v[198:199]
	v_pk_mul_f32 v[8:9], v[8:9], v[202:203]
	v_pk_mul_f32 v[4:5], v[4:5], v[206:207]
	v_pk_mul_f32 v[30:31], v[30:31], v[200:201]
	v_pk_mul_f32 v[26:27], v[26:27], v[204:205]
	v_pk_mul_f32 v[22:23], v[22:23], v[208:209]
	v_pk_mul_f32 v[18:19], v[18:19], v[212:213]
	v_pk_mul_f32 v[14:15], v[14:15], v[200:201]
	v_pk_mul_f32 v[10:11], v[10:11], v[204:205]
	v_pk_mul_f32 v[6:7], v[6:7], v[208:209]
	v_pk_mul_f32 v[2:3], v[2:3], v[212:213]
	v_pk_mul_f32 v[0:1], v[0:1], v[210:211]

.LBB0_349:
	ds_read_b128 v[60:63], v192 offset:96
	ds_read_b128 v[56:59], v192 offset:64
	ds_read_b128 v[48:51], v192
	ds_read_b128 v[52:55], v192 offset:32
	ds_read_b128 v[242:245], v189 offset:60416
	ds_read_b128 v[32:35], v192 offset:128
	ds_read_b128 v[36:39], v192 offset:160
	ds_read_b128 v[40:43], v192 offset:192
	ds_read_b128 v[44:47], v192 offset:224
	ds_read_b128 v[250:253], v189 offset:61440
	s_waitcnt lgkmcnt(10)
	s_barrier
	v_add_u32_e32 v196, s64, v144
	ds_read_b128 v[238:241], v196
	ds_read_b128 v[246:249], v196 offset:512
	s_waitcnt lgkmcnt(1)
	v_mfma_f32_32x32x16_bf16 v[48:63], v[238:241], v[242:245], v[48:63]
	ds_read_b128 v[238:241], v196 offset:2080
	v_max3_f32 v237, v80, s94, v81
	v_max3_f32 v237, v237, v82, v83
	v_add_f32_e32 v198, 0, v198
	v_add_f32_e32 v198, v199, v198
	v_add_f32_e32 v198, v200, v198
	v_add_f32_e32 v198, v201, v198
	v_add_f32_e32 v198, v202, v198
	s_waitcnt lgkmcnt(1)
	v_mfma_f32_32x32x16_bf16 v[32:47], v[246:249], v[242:245], v[32:47]
	ds_read_b128 v[242:245], v196 offset:2592
	ds_read_b128 v[246:249], v189 offset:62464
	v_max3_f32 v237, v237, v84, v85
	v_max3_f32 v237, v237, v86, v87
	v_add_f32_e32 v198, v203, v198
	v_add_f32_e32 v198, v204, v198
	v_add_f32_e32 v198, v205, v198
	v_add_f32_e32 v198, v206, v198
	v_add_f32_e32 v198, v207, v198
	s_waitcnt lgkmcnt(2)
	v_mfma_f32_32x32x16_bf16 v[48:63], v[238:241], v[250:253], v[48:63]
	ds_read_b128 v[238:241], v196 offset:4160
	v_max3_f32 v237, v237, v88, v89
	v_max3_f32 v237, v237, v90, v91
	v_add_f32_e32 v198, v208, v198
	v_add_f32_e32 v198, v209, v198
	v_add_f32_e32 v198, v210, v198
	v_add_f32_e32 v198, v211, v198
	v_add_f32_e32 v198, v212, v198
	s_waitcnt lgkmcnt(2)
	v_mfma_f32_32x32x16_bf16 v[32:47], v[242:245], v[250:253], v[32:47]
	ds_read_b128 v[242:245], v196 offset:4672
	ds_read_b128 v[250:253], v189 offset:63488
	v_max3_f32 v237, v237, v92, v93
	v_max3_f32 v237, v237, v94, v95
	v_add_f32_e32 v198, v213, v198
	v_add_f32_e32 v198, v214, v198
	v_add_f32_e32 v198, v215, v198
	v_add_f32_e32 v198, v216, v198
	v_add_f32_e32 v198, v217, v198
	s_waitcnt lgkmcnt(2)
	v_mfma_f32_32x32x16_bf16 v[48:63], v[238:241], v[246:249], v[48:63]
	ds_read_b128 v[238:241], v196 offset:6240
	v_max3_f32 v237, v237, v64, v65
	v_max3_f32 v237, v237, v66, v67
	v_add_f32_e32 v198, v218, v198
	v_add_f32_e32 v198, v219, v198
	v_add_f32_e32 v198, v220, v198
	v_add_f32_e32 v198, v221, v198
	v_add_f32_e32 v198, v222, v198
	s_waitcnt lgkmcnt(2)
	v_mfma_f32_32x32x16_bf16 v[32:47], v[242:245], v[246:249], v[32:47]
	ds_read_b128 v[242:245], v196 offset:6752
	v_max3_f32 v237, v237, v68, v69
	v_max3_f32 v237, v237, v70, v71
	v_add_f32_e32 v198, v223, v198
	v_add_f32_e32 v198, v224, v198
	v_add_f32_e32 v198, v225, v198
	v_add_f32_e32 v198, v226, v198
	v_add_f32_e32 v198, v227, v198
	s_waitcnt lgkmcnt(1)
	v_mfma_f32_32x32x16_bf16 v[48:63], v[238:241], v[250:253], v[48:63]
	v_max3_f32 v196, v237, v72, v73
	v_max3_f32 v196, v196, v74, v75
	v_add_f32_e32 v198, v228, v198
	v_add_f32_e32 v198, v229, v198
	v_fmac_f32_e32 v198, v191, v197
	s_waitcnt lgkmcnt(0)
	v_mfma_f32_32x32x16_bf16 v[32:47], v[242:245], v[250:253], v[32:47]
	v_max3_f32 v196, v196, v76, v77
	v_max3_f32 v196, v196, v78, v79
	v_mov_b32_e32 v237, v196
	v_mov_b32_e32 v238, v196
	s_nop 1
	v_permlane32_swap_b32_e32 v237, v238
	v_max_f32_e32 v196, v237, v238
	v_add_f32_e32 v237, 0x40c00000, v236
	v_cmp_gt_f32_e32 vcc, v196, v237
	s_nop 1
	v_cndmask_b32_e32 v196, v236, v196, vcc
	v_sub_f32_e32 v237, v236, v196
	v_exp_f32_e32 v237, v237
	s_cbranch_vccz .LBB0_353
	s_and_saveexec_b64 vcc, s[36:37]
	ds_write_b32 v176, v237 offset:58112
	s_or_b64 exec, exec, vcc
	v_add_u32_e32 v236, s75, v108
	ds_read_b128 v[238:241], v236 offset:58208
	ds_read_b128 v[242:245], v236 offset:58176
	ds_read_b128 v[246:249], v236 offset:58144
	ds_read_b128 v[250:253], v236 offset:58112
	s_waitcnt lgkmcnt(3)
	v_pk_mul_f32 v[12:13], v[12:13], v[238:239]
	s_waitcnt lgkmcnt(2)
	v_pk_mul_f32 v[8:9], v[8:9], v[242:243]
	s_waitcnt lgkmcnt(1)
	v_pk_mul_f32 v[4:5], v[4:5], v[246:247]
	v_pk_mul_f32 v[14:15], v[14:15], v[240:241]
	v_pk_mul_f32 v[10:11], v[10:11], v[244:245]
	v_pk_mul_f32 v[6:7], v[6:7], v[248:249]
	s_waitcnt lgkmcnt(0)
	v_pk_mul_f32 v[2:3], v[2:3], v[252:253]
	v_pk_mul_f32 v[0:1], v[0:1], v[250:251]
	v_pk_mul_f32 v[28:29], v[28:29], v[238:239]
	v_pk_mul_f32 v[24:25], v[24:25], v[242:243]
	v_pk_mul_f32 v[20:21], v[20:21], v[246:247]
	v_pk_mul_f32 v[30:31], v[30:31], v[240:241]
	v_pk_mul_f32 v[26:27], v[26:27], v[244:245]
	v_pk_mul_f32 v[22:23], v[22:23], v[248:249]
	v_pk_mul_f32 v[18:19], v[18:19], v[252:253]
	v_pk_mul_f32 v[16:17], v[16:17], v[250:251]
